# re-measure k16 paired (quick timings drifted)
# speedup vs baseline: 1.0041x; 1.0041x over previous
.LBB0_540:
	s_or_b64 exec, exec, s[6:7]
	s_ashr_i32 s9, s8, 31
	v_lshrrev_b32_e32 v8, 3, v112
	s_lshl_b64 s[6:7], s[8:9], 11
	v_xor_b32_e32 v0, v8, v120
	s_add_u32 s6, s60, s6
	v_lshl_add_u32 v9, v0, 4, s18
	s_addc_u32 s7, s61, s7
	s_ashr_i32 s5, s4, 31
	v_lshl_add_u32 v0, v8, 7, v9
	s_lshl_b64 s[4:5], s[4:5], 1
	ds_read_b128 v[0:3], v0
	s_add_u32 s4, s6, s4
	s_addc_u32 s5, s7, s5
	v_lshlrev_b32_e32 v112, 4, v120
	s_waitcnt lgkmcnt(3)
	v_lshl_add_u64 v[4:5], s[4:5], 0, v[112:113]
	v_lshlrev_b32_e32 v112, 11, v8
	v_lshl_add_u64 v[6:7], v[4:5], 0, v[112:113]
	s_waitcnt lgkmcnt(0)
	global_store_dwordx4 v[6:7], v[0:3], off
	v_or_b32_e32 v20, 8, v8
	v_lshl_add_u32 v21, v20, 7, v9
	ds_read_b128 v[16:19], v21
	v_or_b32_e32 v28, 16, v8
	v_lshl_add_u32 v29, v28, 7, v9
	ds_read_b128 v[24:27], v29
	v_or_b32_e32 v36, 24, v8
	v_lshl_add_u32 v37, v36, 7, v9
	ds_read_b128 v[32:35], v37
	v_or_b32_e32 v44, 32, v8
	v_lshl_add_u32 v45, v44, 7, v9
	ds_read_b128 v[40:43], v45
	v_or_b32_e32 v52, 40, v8
	v_lshl_add_u32 v53, v52, 7, v9
	ds_read_b128 v[48:51], v53
	v_lshlrev_b32_e32 v112, 11, v20
	v_lshl_add_u64 v[22:23], v[4:5], 0, v[112:113]
	v_lshlrev_b32_e32 v112, 11, v28
	v_lshl_add_u64 v[30:31], v[4:5], 0, v[112:113]
	v_lshlrev_b32_e32 v112, 11, v36
	v_lshl_add_u64 v[38:39], v[4:5], 0, v[112:113]
	v_lshlrev_b32_e32 v112, 11, v44
	v_lshl_add_u64 v[46:47], v[4:5], 0, v[112:113]
	v_lshlrev_b32_e32 v112, 11, v52
	v_lshl_add_u64 v[54:55], v[4:5], 0, v[112:113]
	s_waitcnt lgkmcnt(4)
	global_store_dwordx4 v[22:23], v[16:19], off
	s_waitcnt lgkmcnt(3)
	global_store_dwordx4 v[30:31], v[24:27], off
	s_waitcnt lgkmcnt(2)
	global_store_dwordx4 v[38:39], v[32:35], off
	s_waitcnt lgkmcnt(1)
	global_store_dwordx4 v[46:47], v[40:43], off
	s_waitcnt lgkmcnt(0)
	global_store_dwordx4 v[54:55], v[48:51], off
	v_or_b32_e32 v20, 48, v8
	v_lshl_add_u32 v21, v20, 7, v9
	ds_read_b128 v[16:19], v21
	v_or_b32_e32 v28, 56, v8
	v_lshl_add_u32 v29, v28, 7, v9
	ds_read_b128 v[24:27], v29
	v_or_b32_e32 v36, 64, v8
	v_lshl_add_u32 v37, v36, 7, v9
	ds_read_b128 v[32:35], v37
	v_or_b32_e32 v44, 0x48, v8
	v_lshl_add_u32 v45, v44, 7, v9
	ds_read_b128 v[40:43], v45
	v_or_b32_e32 v52, 0x50, v8
	v_lshl_add_u32 v53, v52, 7, v9
	ds_read_b128 v[48:51], v53
	v_lshlrev_b32_e32 v112, 11, v20
	v_lshl_add_u64 v[22:23], v[4:5], 0, v[112:113]
	v_lshlrev_b32_e32 v112, 11, v28
	v_lshl_add_u64 v[30:31], v[4:5], 0, v[112:113]
	v_lshlrev_b32_e32 v112, 11, v36
	v_lshl_add_u64 v[38:39], v[4:5], 0, v[112:113]
	v_lshlrev_b32_e32 v112, 11, v44
	v_lshl_add_u64 v[46:47], v[4:5], 0, v[112:113]
	v_lshlrev_b32_e32 v112, 11, v52
	v_lshl_add_u64 v[54:55], v[4:5], 0, v[112:113]
	s_waitcnt lgkmcnt(4)
	global_store_dwordx4 v[22:23], v[16:19], off
	s_waitcnt lgkmcnt(3)
	global_store_dwordx4 v[30:31], v[24:27], off
	s_waitcnt lgkmcnt(2)
	global_store_dwordx4 v[38:39], v[32:35], off
	s_waitcnt lgkmcnt(1)
	global_store_dwordx4 v[46:47], v[40:43], off
	s_waitcnt lgkmcnt(0)
	global_store_dwordx4 v[54:55], v[48:51], off
	v_or_b32_e32 v20, 0x58, v8
	v_lshl_add_u32 v21, v20, 7, v9
	ds_read_b128 v[16:19], v21
	v_or_b32_e32 v28, 0x60, v8
	v_lshl_add_u32 v29, v28, 7, v9
	ds_read_b128 v[24:27], v29
	v_or_b32_e32 v36, 0x68, v8
	v_lshl_add_u32 v37, v36, 7, v9
	ds_read_b128 v[32:35], v37
	v_or_b32_e32 v44, 0x70, v8
	v_lshl_add_u32 v45, v44, 7, v9
	ds_read_b128 v[40:43], v45
	v_or_b32_e32 v52, 0x78, v8
	v_lshl_add_u32 v53, v52, 7, v9
	ds_read_b128 v[48:51], v53
	v_lshlrev_b32_e32 v112, 11, v20
	v_lshl_add_u64 v[22:23], v[4:5], 0, v[112:113]
	v_lshlrev_b32_e32 v112, 11, v28
	v_lshl_add_u64 v[30:31], v[4:5], 0, v[112:113]
	v_lshlrev_b32_e32 v112, 11, v36
	v_lshl_add_u64 v[38:39], v[4:5], 0, v[112:113]
	v_lshlrev_b32_e32 v112, 11, v44
	v_lshl_add_u64 v[46:47], v[4:5], 0, v[112:113]
	v_lshlrev_b32_e32 v112, 11, v52
	v_lshl_add_u64 v[54:55], v[4:5], 0, v[112:113]
	s_waitcnt lgkmcnt(4)
	global_store_dwordx4 v[22:23], v[16:19], off
	s_waitcnt lgkmcnt(3)
	global_store_dwordx4 v[30:31], v[24:27], off
	s_waitcnt lgkmcnt(2)
	global_store_dwordx4 v[38:39], v[32:35], off
	s_waitcnt lgkmcnt(1)
	global_store_dwordx4 v[46:47], v[40:43], off
	s_waitcnt lgkmcnt(0)
	global_store_dwordx4 v[54:55], v[48:51], off
	s_barrier
	s_load_dword s4, s[34:35], 0x0
	s_waitcnt lgkmcnt(0)
	s_add_i32 s14, s4, s14
	s_cmpk_lt_i32 s14, 0x200
	s_cbranch_scc0 .LBB0_559

.LBB0_1073:
	s_or_b64 exec, exec, s[6:7]
	s_ashr_i32 s9, s8, 31
	v_lshrrev_b32_e32 v8, 3, v118
	s_lshl_b64 s[6:7], s[8:9], 11
	v_xor_b32_e32 v0, v8, v119
	s_add_u32 s6, s20, s6
	v_lshl_add_u32 v9, v0, 4, s15
	s_addc_u32 s7, s21, s7
	s_ashr_i32 s5, s4, 31
	v_lshl_add_u32 v0, v8, 7, v9
	s_lshl_b64 s[4:5], s[4:5], 1
	ds_read_b128 v[0:3], v0
	s_add_u32 s4, s6, s4
	s_addc_u32 s5, s7, s5
	v_lshlrev_b32_e32 v128, 4, v119
	s_waitcnt lgkmcnt(3)
	v_lshl_add_u64 v[4:5], s[4:5], 0, v[128:129]
	v_lshlrev_b32_e32 v128, 11, v8
	v_lshl_add_u64 v[6:7], v[4:5], 0, v[128:129]
	s_waitcnt lgkmcnt(0)
	global_store_dwordx4 v[6:7], v[0:3], off
	v_or_b32_e32 v20, 8, v8
	v_lshl_add_u32 v21, v20, 7, v9
	ds_read_b128 v[16:19], v21
	v_or_b32_e32 v28, 16, v8
	v_lshl_add_u32 v29, v28, 7, v9
	ds_read_b128 v[24:27], v29
	v_or_b32_e32 v36, 24, v8
	v_lshl_add_u32 v37, v36, 7, v9
	ds_read_b128 v[32:35], v37
	v_or_b32_e32 v44, 32, v8
	v_lshl_add_u32 v45, v44, 7, v9
	ds_read_b128 v[40:43], v45
	v_or_b32_e32 v52, 40, v8
	v_lshl_add_u32 v53, v52, 7, v9
	ds_read_b128 v[48:51], v53
	v_lshlrev_b32_e32 v128, 11, v20
	v_lshl_add_u64 v[22:23], v[4:5], 0, v[128:129]
	v_lshlrev_b32_e32 v128, 11, v28
	v_lshl_add_u64 v[30:31], v[4:5], 0, v[128:129]
	v_lshlrev_b32_e32 v128, 11, v36
	v_lshl_add_u64 v[38:39], v[4:5], 0, v[128:129]
	v_lshlrev_b32_e32 v128, 11, v44
	v_lshl_add_u64 v[46:47], v[4:5], 0, v[128:129]
	v_lshlrev_b32_e32 v128, 11, v52
	v_lshl_add_u64 v[54:55], v[4:5], 0, v[128:129]
	s_waitcnt lgkmcnt(4)
	global_store_dwordx4 v[22:23], v[16:19], off
	s_waitcnt lgkmcnt(3)
	global_store_dwordx4 v[30:31], v[24:27], off
	s_waitcnt lgkmcnt(2)
	global_store_dwordx4 v[38:39], v[32:35], off
	s_waitcnt lgkmcnt(1)
	global_store_dwordx4 v[46:47], v[40:43], off
	s_waitcnt lgkmcnt(0)
	global_store_dwordx4 v[54:55], v[48:51], off
	v_or_b32_e32 v20, 48, v8
	v_lshl_add_u32 v21, v20, 7, v9
	ds_read_b128 v[16:19], v21
	v_or_b32_e32 v28, 56, v8
	v_lshl_add_u32 v29, v28, 7, v9
	ds_read_b128 v[24:27], v29
	v_or_b32_e32 v36, 64, v8
	v_lshl_add_u32 v37, v36, 7, v9
	ds_read_b128 v[32:35], v37
	v_or_b32_e32 v44, 0x48, v8
	v_lshl_add_u32 v45, v44, 7, v9
	ds_read_b128 v[40:43], v45
	v_or_b32_e32 v52, 0x50, v8
	v_lshl_add_u32 v53, v52, 7, v9
	ds_read_b128 v[48:51], v53
	v_lshlrev_b32_e32 v128, 11, v20
	v_lshl_add_u64 v[22:23], v[4:5], 0, v[128:129]
	v_lshlrev_b32_e32 v128, 11, v28
	v_lshl_add_u64 v[30:31], v[4:5], 0, v[128:129]
	v_lshlrev_b32_e32 v128, 11, v36
	v_lshl_add_u64 v[38:39], v[4:5], 0, v[128:129]
	v_lshlrev_b32_e32 v128, 11, v44
	v_lshl_add_u64 v[46:47], v[4:5], 0, v[128:129]
	v_lshlrev_b32_e32 v128, 11, v52
	v_lshl_add_u64 v[54:55], v[4:5], 0, v[128:129]
	s_waitcnt lgkmcnt(4)
	global_store_dwordx4 v[22:23], v[16:19], off
	s_waitcnt lgkmcnt(3)
	global_store_dwordx4 v[30:31], v[24:27], off
	s_waitcnt lgkmcnt(2)
	global_store_dwordx4 v[38:39], v[32:35], off
	s_waitcnt lgkmcnt(1)
	global_store_dwordx4 v[46:47], v[40:43], off
	s_waitcnt lgkmcnt(0)
	global_store_dwordx4 v[54:55], v[48:51], off
	v_or_b32_e32 v20, 0x58, v8
	v_lshl_add_u32 v21, v20, 7, v9
	ds_read_b128 v[16:19], v21
	v_or_b32_e32 v28, 0x60, v8
	v_lshl_add_u32 v29, v28, 7, v9
	ds_read_b128 v[24:27], v29
	v_or_b32_e32 v36, 0x68, v8
	v_lshl_add_u32 v37, v36, 7, v9
	ds_read_b128 v[32:35], v37
	v_or_b32_e32 v44, 0x70, v8
	v_lshl_add_u32 v45, v44, 7, v9
	ds_read_b128 v[40:43], v45
	v_or_b32_e32 v52, 0x78, v8
	v_lshl_add_u32 v53, v52, 7, v9
	ds_read_b128 v[48:51], v53
	v_lshlrev_b32_e32 v128, 11, v20
	v_lshl_add_u64 v[22:23], v[4:5], 0, v[128:129]
	v_lshlrev_b32_e32 v128, 11, v28
	v_lshl_add_u64 v[30:31], v[4:5], 0, v[128:129]
	v_lshlrev_b32_e32 v128, 11, v36
	v_lshl_add_u64 v[38:39], v[4:5], 0, v[128:129]
	v_lshlrev_b32_e32 v128, 11, v44
	v_lshl_add_u64 v[46:47], v[4:5], 0, v[128:129]
	v_lshlrev_b32_e32 v128, 11, v52
	v_lshl_add_u64 v[54:55], v[4:5], 0, v[128:129]
	s_waitcnt lgkmcnt(4)
	global_store_dwordx4 v[22:23], v[16:19], off
	s_waitcnt lgkmcnt(3)
	global_store_dwordx4 v[30:31], v[24:27], off
	s_waitcnt lgkmcnt(2)
	global_store_dwordx4 v[38:39], v[32:35], off
	s_waitcnt lgkmcnt(1)
	global_store_dwordx4 v[46:47], v[40:43], off
	s_waitcnt lgkmcnt(0)
	global_store_dwordx4 v[54:55], v[48:51], off
	s_barrier
	s_load_dword s4, s[34:35], 0x0
	s_waitcnt lgkmcnt(0)
	s_add_i32 s14, s4, s14
	s_cmpk_lt_i32 s14, 0x200
	s_cbranch_scc0 .LBB0_1092
